# ret_out-item-loads-K-V-issued-with-Q-one-round-trip
# speedup vs baseline: 1.0197x; 1.0038x over previous
; #define LAS __attribute__((address_space(3)))
; __device__ __forceinline__ void unpack8(u32x4 u, float* o) { o[0] = bflo(u.x); o[1] = bfhi(u.x); o[2] = bflo(u.y); o[3] = bfhi(u.y); o[4] = bflo(u.z); o[5] = bfhi(u.z); o[6] = bflo(u.w); o[7] = bfhi(u.w); }
; __device__ __forceinline__ u32x4 pack8u(const float* f) { u32x4 u; u.x = pk2(f[0], f[1]); u.y = pk2(f[2], f[3]); u.z = pk2(f[4], f[5]); u.w = pk2(f[6], f[7]); return u; }
; __device__ __forceinline__ void rot8(const bf16* src, const float* rot, int pos, int part, float scale, float* o1, float* o2) {
;     float x1[8], x2[8]; unpack8(*(const u32x4*)(src + 8 * part), x1); unpack8(*(const u32x4*)(src + 32 + 8 * part), x2);
;     const float* cs = rot + (size_t)pos * 32 + 8 * part; const float* sn = rot + (size_t)2048 * 32 + (size_t)pos * 32 + 8 * part;
;     const f32x4 c0 = *(const f32x4*)cs, c1 = *(const f32x4*)(cs + 4), s0 = *(const f32x4*)sn, s1 = *(const f32x4*)(sn + 4);
;     const float cv[8] = {c0.x, c0.y, c0.z, c0.w, c1.x, c1.y, c1.z, c1.w}, sv[8] = {s0.x, s0.y, s0.z, s0.w, s1.x, s1.y, s1.z, s1.w};
; #pragma unroll
;     for (int i = 0; i < 8; ++i) { o1[i] = (x1[i] * cv[i] - x2[i] * sv[i]) * scale; o2[i] = (x1[i] * sv[i] + x2[i] * cv[i]) * scale; }
; }
; __device__ __forceinline__ void ret_out_phase(int l, LAS unsigned char* lds, int wave, int lane_) {
;     ...
;     for (int it = blockIdx.x; it < BATCH * 8 * NRC; it += gridDim.x) {
;         const int j = it % NRC, bh = it / NRC, b = bh >> 3, h = bh & 7;
;         const float l2g = ret_log2g(h);
;         const __amdgpu_buffer_rsrc_t strs = __builtin_amdgcn_make_buffer_rsrc((void*)(ws + OFF_ST), 0, 0x7fffffff, 0x00027000);
;         const unsigned sfo = (unsigned)(((bh * NRC + j) * 2 + 0) * 8192 * 2);
;         u32x4 sfv[4][2], sbv[4][2];
;     ...
;         RET_LD_STATES(0);
;         {
;             const int m = tid >> 2, part = tid & 3; const int pos = j * RC + m;
;             const bf16* src = rawB + ((size_t)b * SEQ + pos) * 2048 + h * 64;
;             float o1[8], o2[8];
;             rot8(src, rot, pos, part, 0.125f, o1, o2);
;             *(LAS u32x4*)(Qs + m * QP + 8 * part) = pack8u(o1); *(LAS u32x4*)(Qs + m * QP + 32 + 8 * part) = pack8u(o2);
;             rot8(src + 512, rot, pos, part, 1.0f, o1, o2);
;             *(LAS u32x4*)(Ks + m * QP + 8 * part) = pack8u(o1); *(LAS u32x4*)(Ks + m * QP + 32 + 8 * part) = pack8u(o2);
.LBB0_632:
	s_ashr_i32 s34, s46, 31
	s_lshr_b32 s34, s34, 28
	s_add_i32 s36, s46, s34
	s_ashr_i32 s37, s36, 4
	s_and_b32 s42, s37, 7
	v_cvt_f32_ubyte0_e32 v4, s42
	v_sub_f32_e32 v4, 0xc0a00000, v4
	v_cmp_gt_f32_e32 vcc, s50, v4
	s_and_b64 s[34:35], vcc, exec
	s_cselect_b32 s34, 0xffffffc0, 0
	v_cndmask_b32_e32 v5, 0, v206, vcc
	v_add_f32_e32 v4, v4, v5
	v_exp_f32_e32 v4, v4
	s_lshl_b32 s35, s37, 11
	v_add_u32_e32 v12, 0xffff8800, v161
	s_waitcnt vmcnt(5)
	v_add_u32_e32 v20, 0xffffcfc0, v161
	v_ldexp_f32 v76, v4, s34
	s_ashr_i32 s34, s36, 7
	s_sub_i32 s36, s29, s35
	v_add_u32_e32 v78, s36, v94
	s_ashr_i32 s35, s34, 31
	s_lshl_b64 s[34:35], s[34:35], 11
	v_ashrrev_i32_e32 v79, 31, v78
	v_lshl_add_u64 v[68:69], s[34:35], 0, v[78:79]
	v_fmamk_f32 v77, v76, 0x3e800000, v201
	v_lshlrev_b64 v[68:69], 12, v[68:69]
	v_pk_mul_f32 v[4:5], v[76:77], v[76:77] op_sel_hi:[0,1]
	buffer_load_dwordx4 v[16:19], v12, s[60:63], 0 offen sc0 sc1
	s_waitcnt vmcnt(4)
	v_add_u32_e32 v28, 0xffff9000, v161
	buffer_load_dwordx4 v[20:23], v20, s[60:63], 0 offen sc0 sc1
	v_add_u32_e32 v12, 0xffffc800, v161
	v_add_u32_e32 v44, 0xffff9800, v161
	v_add_u32_e32 v52, 0xffffdfc0, v161
	v_lshl_add_u64 v[68:69], s[44:45], 0, v[68:69]
	s_lshl_b32 s96, s42, 7
	v_add_f32_e32 v5, 0.5, v5
	buffer_load_dwordx4 v[24:27], v12, s[60:63], 0 offen sc0 sc1
	buffer_load_dwordx4 v[32:35], v28, s[60:63], 0 offen sc0 sc1
	v_add_u32_e32 v12, 0xffff8fc0, v161
	v_add_u32_e32 v28, 0xffffd000, v161
	buffer_load_dwordx4 v[48:51], v44, s[60:63], 0 offen sc0 sc1
	v_add_u32_e32 v60, 0xffffa000, v161
	buffer_load_dwordx4 v[52:55], v52, s[60:63], 0 offen sc0 sc1
	v_add_u32_e32 v44, 0xffffd800, v161
	v_lshl_add_u64 v[68:69], v[68:69], 0, s[96:97]
	v_fmac_f32_e32 v76, v4, v5
	v_add_u32_e32 v4, 0xffff87c0, v161
	v_add_u32_e32 v8, 0xffffc7c0, v161
	buffer_load_dwordx4 v[12:15], v12, s[60:63], 0 offen sc0 sc1
	s_waitcnt vmcnt(8)
	v_add_u32_e32 v36, 0xffffd7c0, v161
	buffer_load_dwordx4 v[40:43], v28, s[60:63], 0 offen sc0 sc1
	v_add_u32_e32 v28, 0xffff97c0, v161
	buffer_load_dwordx4 v[56:59], v44, s[60:63], 0 offen sc0 sc1
	v_add_u32_e32 v64, 0xffffe000, v161
	buffer_load_dwordx4 v[60:63], v60, s[60:63], 0 offen sc0 sc1
	v_add_u32_e32 v44, 0xffff9fc0, v161
	v_lshl_add_u64 v[90:91], v[68:69], 0, v[2:3]
	v_lshlrev_b64 v[78:79], 7, v[78:79]
	buffer_load_dwordx4 v[4:7], v4, s[60:63], 0 offen sc0 sc1
	v_lshl_add_u64 v[82:83], v[96:97], 0, v[78:79]
	buffer_load_dwordx4 v[8:11], v8, s[60:63], 0 offen sc0 sc1
	v_lshl_add_u64 v[110:111], v[98:99], 0, v[78:79]
	buffer_load_dwordx4 v[28:31], v28, s[60:63], 0 offen sc0 sc1
	s_ashr_i32 s37, s36, 31
	buffer_load_dwordx4 v[36:39], v36, s[60:63], 0 offen sc0 sc1
	s_add_u32 s34, s34, s36
	buffer_load_dwordx4 v[44:47], v44, s[60:63], 0 offen sc0 sc1
	s_addc_u32 s35, s35, s37
	buffer_load_dwordx4 v[64:67], v64, s[60:63], 0 offen sc0 sc1
	s_nop 0
	global_load_dwordx4 v[68:71], v[90:91], off
	global_load_dwordx4 v[72:75], v[90:91], off offset:64
	global_load_dwordx4 v[78:81], v[82:83], off offset:16
	s_nop 0
	global_load_dwordx4 v[82:85], v[82:83], off
	s_nop 0
	global_load_dwordx4 v[86:89], v[110:111], off offset:16
	s_nop 0
	global_load_dwordx4 v[110:113], v[110:111], off
	s_lshl_b32 s96, s42, 8
	v_mov_b32_e32 v109, v3
	s_add_u32 s36, s6, s96
	s_addc_u32 s37, s7, 0
	global_load_dwordx4 v[224:227], v[90:91], off offset:1024
	global_load_dwordx4 v[228:231], v[90:91], off offset:1088
	v_lshl_add_u64 v[248:249], s[34:35], 0, v[94:95]
	v_lshlrev_b64 v[248:249], 12, v[248:249]
	v_lshl_add_u64 v[248:249], s[44:45], 0, v[248:249]
	v_lshl_add_u64 v[248:249], v[248:249], 0, s[96:97]
	v_lshl_add_u64 v[248:249], v[248:249], 0, v[108:109]
	global_load_dwordx4 v[232:235], v[248:249], off offset:2048
	global_load_dwordx4 v[236:239], v[248:249], off offset:2064
	global_load_dwordx4 v[240:243], v[248:249], off offset:2080
	global_load_dwordx4 v[244:247], v[248:249], off offset:2096
	s_waitcnt vmcnt(11)
	v_lshlrev_b32_e32 v114, 16, v68
	s_waitcnt vmcnt(10)
	v_lshlrev_b32_e32 v116, 16, v72
	v_and_b32_e32 v117, 0xffff0000, v72
	v_and_b32_e32 v115, 0xffff0000, v68
	s_waitcnt vmcnt(6)
	v_pk_mul_f32 v[182:183], v[110:111], v[116:117]
	v_lshlrev_b32_e32 v72, 16, v73
	v_pk_fma_f32 v[182:183], v[82:83], v[114:115], v[182:183] neg_lo:[0,0,1] neg_hi:[0,0,1]
	v_pk_mul_f32 v[114:115], v[110:111], v[114:115]
	v_and_b32_e32 v73, 0xffff0000, v73
	v_pk_fma_f32 v[114:115], v[82:83], v[116:117], v[114:115]
	v_lshlrev_b32_e32 v68, 16, v69
	v_and_b32_e32 v69, 0xffff0000, v69
	v_pk_mul_f32 v[116:117], v[112:113], v[72:73]
	v_lshlrev_b32_e32 v184, 16, v74
	v_pk_fma_f32 v[116:117], v[84:85], v[68:69], v[116:117] neg_lo:[0,0,1] neg_hi:[0,0,1]
	v_pk_mul_f32 v[68:69], v[112:113], v[68:69]
	v_and_b32_e32 v185, 0xffff0000, v74
	v_pk_fma_f32 v[68:69], v[84:85], v[72:73], v[68:69]
	v_pk_mul_f32 v[186:187], v[86:87], v[184:185]
	v_pk_mul_f32 v[72:73], v[68:69], s[88:89] op_sel_hi:[1,0]
	v_lshlrev_b32_e32 v68, 16, v70
	v_and_b32_e32 v69, 0xffff0000, v70
	v_pk_fma_f32 v[186:187], v[78:79], v[68:69], v[186:187] neg_lo:[0,0,1] neg_hi:[0,0,1]
	v_pk_mul_f32 v[68:69], v[86:87], v[68:69]
	v_lshlrev_b32_e32 v70, 16, v75
	v_pk_fma_f32 v[68:69], v[78:79], v[184:185], v[68:69]
	v_pk_mul_f32 v[182:183], v[182:183], s[88:89] op_sel_hi:[1,0]
	v_pk_mul_f32 v[184:185], v[68:69], s[88:89] op_sel_hi:[1,0]
	v_lshlrev_b32_e32 v68, 16, v71
	v_and_b32_e32 v69, 0xffff0000, v71
	v_and_b32_e32 v71, 0xffff0000, v75
	v_pk_mul_f32 v[74:75], v[88:89], v[70:71]
	v_pk_mul_f32 v[116:117], v[116:117], s[88:89] op_sel_hi:[1,0]
	v_pk_fma_f32 v[74:75], v[80:81], v[68:69], v[74:75] neg_lo:[0,0,1] neg_hi:[0,0,1]
	v_pk_mul_f32 v[68:69], v[88:89], v[68:69]
	v_pk_mul_f32 v[186:187], v[186:187], s[88:89] op_sel_hi:[1,0]
	v_pk_mul_f32 v[74:75], v[74:75], s[88:89] op_sel_hi:[1,0]
	v_pk_fma_f32 v[68:69], v[80:81], v[70:71], v[68:69]
	v_pk_mul_f32 v[114:115], v[114:115], s[88:89] op_sel_hi:[1,0]
	v_pk_mul_f32 v[188:189], v[68:69], s[88:89] op_sel_hi:[1,0]
	v_cvt_pk_bf16_f32 v68, v182, v183
	v_cvt_pk_bf16_f32 v69, v116, v117
	v_cvt_pk_bf16_f32 v70, v186, v187
	v_cvt_pk_bf16_f32 v71, v74, v75
	ds_write_b128 v118, v[68:71]
	v_cvt_pk_bf16_f32 v68, v114, v115
	v_cvt_pk_bf16_f32 v69, v72, v73
	v_cvt_pk_bf16_f32 v70, v184, v185
	v_cvt_pk_bf16_f32 v71, v188, v189
	ds_write_b128 v118, v[68:71] offset:64
	s_waitcnt vmcnt(5)
; #define LAS __attribute__((address_space(3)))
; #define LDS_WAIT() asm volatile("s_waitcnt lgkmcnt(0)" ::: "memory")
; __device__ __forceinline__ unsigned f2bf(float f) { return cvtpk(f, 0.f) & 0xffffu; }
; __device__ __forceinline__ u32x4 pack8u(const float* f) { u32x4 u; u.x = pk2(f[0], f[1]); u.y = pk2(f[2], f[3]); u.z = pk2(f[4], f[5]); u.w = pk2(f[6], f[7]); return u; }
; #define MFMA16(a, b, c) __builtin_amdgcn_mfma_f32_16x16x32_bf16((a), (b), (c), 0, 0, 0)
; __device__ __forceinline__ void stage_vt(const bf16* rawB, int b, int h, int j, LAS bf16* Vt, int tid) {
;     const int m = tid >> 2, part = tid & 3;
;     const bf16* src = rawB + ((size_t)b * SEQ + j * RC + m) * 2048 + 1024 + h * 128 + 32 * part;
; #pragma unroll
;     for (int q = 0; q < 4; ++q) { float f[8]; const u32x4 u = *(const u32x4*)(src + 8 * q);
;         const unsigned w[4] = {u.x, u.y, u.z, u.w};
; #pragma unroll
;         for (int i = 0; i < 4; ++i) { Vt[(32 * part + 8 * q + 2 * i) * KP + m] = (bf16)(w[i] & 0xffffu); Vt[(32 * part + 8 * q + 2 * i + 1) * KP + m] = (bf16)(w[i] >> 16); }
;         (void)f; }
; }
; __device__ __forceinline__ void ret_out_phase(int l, LAS unsigned char* lds, int wave, int lane_) {
;     ...
;             rot8(src + 512, rot, pos, part, 1.0f, o1, o2);
;             *(LAS u32x4*)(Ks + m * QP + 8 * part) = pack8u(o1); *(LAS u32x4*)(Ks + m * QP + 32 + 8 * part) = pack8u(o2);
;             stage_vt(rawB, b, h, j, Vt, tid);
;         }
;         LDS_WAIT(); __syncthreads();
;         bf16x8 aq[2];
; #pragma unroll
;         for (int ks = 0; ks < 2; ++ks) aq[ks] = *(const LAS bf16x8*)(Qs + (16 * wave + fr) * QP + 32 * ks + 8 * fq);
; #pragma unroll
;         for (int nb = 0; nb < 8; ++nb) {
;             f32x4 sc = {0.f, 0.f, 0.f, 0.f};
; #pragma unroll
;             for (int ks = 0; ks < 2; ++ks) { const bf16x8 bk = *(const LAS bf16x8*)(Ks + (nb * 16 + fr) * QP + 32 * ks + 8 * fq); sc = MFMA16(aq[ks], bk, sc); }
; #pragma unroll
;             for (int i = 0; i < 4; ++i) { const int n = 16 * wave + 4 * fq + i, mk = nb * 16 + fr; const int d = n > mk ? n - mk : mk - n;
;                 Pw[(4 * fq + i) * KP + mk] = (bf16)f2bf(sc[i] * __builtin_amdgcn_exp2f(l2g * (float)d)); }
;         }
;         LDS_WAIT(); asm volatile("" ::: "memory");
	v_lshlrev_b32_e32 v90, 16, v224
	s_waitcnt vmcnt(4)
	v_lshlrev_b32_e32 v114, 16, v228
	v_and_b32_e32 v115, 0xffff0000, v228
	v_and_b32_e32 v91, 0xffff0000, v224
	v_pk_mul_f32 v[116:117], v[110:111], v[114:115]
	v_lshlrev_b32_e32 v228, 16, v229
	v_pk_fma_f32 v[116:117], v[82:83], v[90:91], v[116:117] neg_lo:[0,0,1] neg_hi:[0,0,1]
	v_pk_mul_f32 v[82:83], v[82:83], v[114:115]
	v_and_b32_e32 v229, 0xffff0000, v229
	v_pk_fma_f32 v[82:83], v[110:111], v[90:91], v[82:83]
	v_lshlrev_b32_e32 v224, 16, v225
	v_and_b32_e32 v225, 0xffff0000, v225
	v_pk_mul_f32 v[90:91], v[112:113], v[228:229]
	v_pk_mul_f32 v[228:229], v[84:85], v[228:229]
	v_pk_fma_f32 v[90:91], v[84:85], v[224:225], v[90:91] neg_lo:[0,0,1] neg_hi:[0,0,1]
	v_lshlrev_b32_e32 v84, 16, v230
	v_and_b32_e32 v85, 0xffff0000, v230
	v_pk_fma_f32 v[228:229], v[112:113], v[224:225], v[228:229]
	v_lshlrev_b32_e32 v224, 16, v226
	v_and_b32_e32 v225, 0xffff0000, v226
	v_pk_mul_f32 v[110:111], v[86:87], v[84:85]
	v_lshlrev_b32_e32 v226, 16, v231
	v_pk_fma_f32 v[110:111], v[78:79], v[224:225], v[110:111] neg_lo:[0,0,1] neg_hi:[0,0,1]
	v_pk_mul_f32 v[78:79], v[78:79], v[84:85]
	v_mul_f32_e32 v84, 0xbfb8aa3b, v76
	v_pk_fma_f32 v[78:79], v[86:87], v[224:225], v[78:79]
	v_lshlrev_b32_e32 v224, 16, v227
	v_and_b32_e32 v225, 0xffff0000, v227
	v_and_b32_e32 v227, 0xffff0000, v231
	v_pk_mul_f32 v[230:231], v[88:89], v[226:227]
	v_pk_mul_f32 v[226:227], v[80:81], v[226:227]
	v_pk_fma_f32 v[230:231], v[80:81], v[224:225], v[230:231] neg_lo:[0,0,1] neg_hi:[0,0,1]
	v_pk_fma_f32 v[80:81], v[88:89], v[224:225], v[226:227]
	v_cvt_pk_bf16_f32 v224, v116, v117
	v_cvt_pk_bf16_f32 v225, v90, v91
	v_cvt_pk_bf16_f32 v226, v110, v111
	v_cvt_pk_bf16_f32 v227, v230, v231
	ds_write_b128 v118, v[224:227] offset:18432
	v_cvt_pk_bf16_f32 v224, v82, v83
	v_cvt_pk_bf16_f32 v225, v228, v229
	v_cvt_pk_bf16_f32 v226, v78, v79
	v_cvt_pk_bf16_f32 v227, v80, v81
	ds_write_b128 v118, v[224:227] offset:18496
	s_waitcnt vmcnt(3)
	ds_write_b16 v119, v232 offset:36864
	ds_write_b16_d16_hi v119, v232 offset:37136
	ds_write_b16 v119, v233 offset:37408
	ds_write_b16_d16_hi v119, v233 offset:37680
	ds_write_b16 v119, v234 offset:37952
	ds_write_b16_d16_hi v119, v234 offset:38224
	ds_write_b16 v119, v235 offset:38496
	ds_write_b16_d16_hi v119, v235 offset:38768
	s_waitcnt vmcnt(2)
	ds_write_b16 v119, v236 offset:39040
	ds_write_b16_d16_hi v119, v236 offset:39312
	ds_write_b16 v119, v237 offset:39584
	ds_write_b16_d16_hi v119, v237 offset:39856
	ds_write_b16 v119, v238 offset:40128
	ds_write_b16_d16_hi v119, v238 offset:40400
	ds_write_b16 v119, v239 offset:40672
	ds_write_b16_d16_hi v119, v239 offset:40944
	s_waitcnt vmcnt(1)
	ds_write_b16 v119, v240 offset:41216
	ds_write_b16_d16_hi v119, v240 offset:41488
	ds_write_b16 v119, v241 offset:41760
	ds_write_b16_d16_hi v119, v241 offset:42032
	ds_write_b16 v119, v242 offset:42304
	ds_write_b16_d16_hi v119, v242 offset:42576
	ds_write_b16 v119, v243 offset:42848
	ds_write_b16_d16_hi v119, v243 offset:43120
	s_waitcnt vmcnt(0)
	ds_write_b16 v119, v244 offset:43392
	ds_write_b16_d16_hi v119, v244 offset:43664
	ds_write_b16 v119, v245 offset:43936
	ds_write_b16_d16_hi v119, v245 offset:44208
	ds_write_b16 v119, v246 offset:44480
	ds_write_b16_d16_hi v119, v246 offset:44752
	ds_write_b16 v119, v247 offset:45024
	ds_write_b16_d16_hi v119, v247 offset:45296
	s_waitcnt lgkmcnt(0)
	s_waitcnt lgkmcnt(0)
	s_barrier
	ds_read_b128 v[72:75], v162
	ds_read_b128 v[68:71], v162 offset:64
	ds_read_b128 v[76:79], v163 offset:18432
	ds_read_b128 v[80:83], v163 offset:18496
	s_waitcnt lgkmcnt(1)
	v_mfma_f32_16x16x32_bf16 v[76:79], v[72:75], v[76:79], 0
	v_add_u32_e32 v109, 0xffffa7c0, v161
	s_waitcnt lgkmcnt(0)
	v_mfma_f32_16x16x32_bf16 v[76:79], v[68:71], v[80:83], v[76:79]
	v_mul_f32_e32 v80, v84, v121
	v_exp_f32_e32 v80, v80
	v_mfma_f32_16x16x32_bf16 v[4:7], v[72:75], v[4:7], 0
	v_mfma_f32_16x16x32_bf16 v[8:11], v[72:75], v[8:11], 0
	s_nop 3
	v_mul_f32_e32 v76, v80, v76
	v_cvt_pk_bf16_f32 v76, v76, s0
	ds_write_b16 v167, v76
	v_mul_f32_e32 v76, v84, v122
	v_exp_f32_e32 v76, v76
	v_mfma_f32_16x16x32_bf16 v[4:7], v[68:71], v[16:19], v[4:7]
	v_mul_f32_e32 v76, v76, v77
	v_cvt_pk_bf16_f32 v76, v76, s0
	ds_write_b16 v167, v76 offset:272
	v_mul_f32_e32 v76, v84, v123
	v_exp_f32_e32 v76, v76
	v_mfma_f32_16x16x32_bf16 v[16:19], v[68:71], v[24:27], v[8:11]
	v_mul_f32_e32 v76, v76, v78
	v_cvt_pk_bf16_f32 v76, v76, s0
	ds_write_b16 v167, v76 offset:544
	v_mul_f32_e32 v76, v84, v124
	v_exp_f32_e32 v76, v76
	v_mfma_f32_16x16x32_bf16 v[10:13], v[72:75], v[12:15], 0
	v_mul_f32_e32 v76, v76, v79
	v_cvt_pk_bf16_f32 v76, v76, s0
	ds_write_b16 v167, v76 offset:816
	ds_read_b128 v[76:79], v163 offset:20736
	ds_read_b128 v[80:83], v163 offset:20800
	s_waitcnt lgkmcnt(1)
	v_mfma_f32_16x16x32_bf16 v[76:79], v[72:75], v[76:79], 0
	s_waitcnt lgkmcnt(0)
	v_mfma_f32_16x16x32_bf16 v[76:79], v[68:71], v[80:83], v[76:79]
	v_mul_f32_e32 v80, v84, v125
	v_exp_f32_e32 v80, v80
	v_mfma_f32_16x16x32_bf16 v[10:13], v[68:71], v[32:35], v[10:13]
	s_nop 4
	v_mul_f32_e32 v76, v80, v76
	v_cvt_pk_bf16_f32 v76, v76, s0
	ds_write_b16 v167, v76 offset:32
	v_mul_f32_e32 v76, v84, v126
	v_exp_f32_e32 v76, v76
	s_nop 0
	v_mul_f32_e32 v76, v76, v77
	v_cvt_pk_bf16_f32 v76, v76, s0
	ds_write_b16 v167, v76 offset:304
	v_mul_f32_e32 v76, v84, v127
	v_exp_f32_e32 v76, v76
	s_nop 0
	v_mul_f32_e32 v76, v76, v78
	v_cvt_pk_bf16_f32 v76, v76, s0
	ds_write_b16 v167, v76 offset:576
	v_mul_f32_e32 v76, v84, v128
	v_exp_f32_e32 v76, v76
	s_nop 0
	v_mul_f32_e32 v76, v76, v79
	v_cvt_pk_bf16_f32 v76, v76, s0
	ds_write_b16 v167, v76 offset:848
	ds_read_b128 v[76:79], v163 offset:23040
	ds_read_b128 v[80:83], v163 offset:23104
	s_waitcnt lgkmcnt(1)
; #define LAS __attribute__((address_space(3)))
; #define LDS_WAIT() asm volatile("s_waitcnt lgkmcnt(0)" ::: "memory")
; __device__ __forceinline__ unsigned f2bf(float f) { return cvtpk(f, 0.f) & 0xffffu; }
; #define MFMA16(a, b, c) __builtin_amdgcn_mfma_f32_16x16x32_bf16((a), (b), (c), 0, 0, 0)
; __device__ __forceinline__ void ret_out_phase(int l, LAS unsigned char* lds, int wave, int lane_) {
;     ...
;         for (int nb = 0; nb < 8; ++nb) {
;             f32x4 sc = {0.f, 0.f, 0.f, 0.f};
; #pragma unroll
;             for (int ks = 0; ks < 2; ++ks) { const bf16x8 bk = *(const LAS bf16x8*)(Ks + (nb * 16 + fr) * QP + 32 * ks + 8 * fq); sc = MFMA16(aq[ks], bk, sc); }
; #pragma unroll
;             for (int i = 0; i < 4; ++i) { const int n = 16 * wave + 4 * fq + i, mk = nb * 16 + fr; const int d = n > mk ? n - mk : mk - n;
;                 Pw[(4 * fq + i) * KP + mk] = (bf16)f2bf(sc[i] * __builtin_amdgcn_exp2f(l2g * (float)d)); }
;         }
;         LDS_WAIT(); asm volatile("" ::: "memory");
;         f32x4 y1[8];
;         f32x4 xfv, xbv;
; #pragma unroll
;         for (int i = 0; i < 4; ++i) { const int nl = 16 * wave + 4 * fq + i; xfv[i] = __builtin_amdgcn_exp2f(l2g * (float)(nl + 1)); xbv[i] = __builtin_amdgcn_exp2f(l2g * (float)(RC - nl)); }
	v_mfma_f32_16x16x32_bf16 v[76:79], v[72:75], v[76:79], 0
	s_waitcnt lgkmcnt(0)
	v_mfma_f32_16x16x32_bf16 v[76:79], v[68:71], v[80:83], v[76:79]
	v_mul_f32_e32 v80, v84, v129
	v_exp_f32_e32 v80, v80
	s_nop 5
	v_mul_f32_e32 v76, v80, v76
	v_cvt_pk_bf16_f32 v76, v76, s0
	ds_write_b16 v167, v76 offset:64
	v_mul_f32_e32 v76, v84, v130
	v_exp_f32_e32 v76, v76
	s_nop 0
	v_mul_f32_e32 v76, v76, v77
	v_cvt_pk_bf16_f32 v76, v76, s0
	ds_write_b16 v167, v76 offset:336
	v_mul_f32_e32 v76, v84, v131
	v_exp_f32_e32 v76, v76
	s_nop 0
	v_mul_f32_e32 v76, v76, v78
	v_cvt_pk_bf16_f32 v76, v76, s0
	ds_write_b16 v167, v76 offset:608
	v_mul_f32_e32 v76, v84, v132
	v_exp_f32_e32 v76, v76
	s_nop 0
	v_mul_f32_e32 v76, v76, v79
	v_cvt_pk_bf16_f32 v76, v76, s0
	ds_write_b16 v167, v76 offset:880
	ds_read_b128 v[76:79], v163 offset:25344
	ds_read_b128 v[80:83], v163 offset:25408
	s_waitcnt lgkmcnt(1)
	v_mfma_f32_16x16x32_bf16 v[76:79], v[72:75], v[76:79], 0
	s_waitcnt lgkmcnt(0)
	v_mfma_f32_16x16x32_bf16 v[76:79], v[68:71], v[80:83], v[76:79]
	v_mul_f32_e32 v80, v84, v133
	v_exp_f32_e32 v80, v80
	s_nop 5
	v_mul_f32_e32 v76, v80, v76
	v_cvt_pk_bf16_f32 v76, v76, s0
	ds_write_b16 v167, v76 offset:96
	v_mul_f32_e32 v76, v84, v134
	v_exp_f32_e32 v76, v76
	s_nop 0
	v_mul_f32_e32 v76, v76, v77
	v_cvt_pk_bf16_f32 v76, v76, s0
	ds_write_b16 v167, v76 offset:368
	v_mul_f32_e32 v76, v84, v135
	v_exp_f32_e32 v76, v76
	s_nop 0
	v_mul_f32_e32 v76, v76, v78
	v_cvt_pk_bf16_f32 v76, v76, s0
	ds_write_b16 v167, v76 offset:640
	v_mul_f32_e32 v76, v84, v136
	v_exp_f32_e32 v76, v76
	s_nop 0
	v_mul_f32_e32 v76, v76, v79
	v_cvt_pk_bf16_f32 v76, v76, s0
	ds_write_b16 v167, v76 offset:912
	ds_read_b128 v[76:79], v163 offset:27648
	ds_read_b128 v[80:83], v163 offset:27712
	s_waitcnt lgkmcnt(1)
	v_mfma_f32_16x16x32_bf16 v[76:79], v[72:75], v[76:79], 0
	s_waitcnt lgkmcnt(0)
	v_mfma_f32_16x16x32_bf16 v[76:79], v[68:71], v[80:83], v[76:79]
	v_mul_f32_e32 v80, v84, v137
	v_exp_f32_e32 v80, v80
	s_nop 5
	v_mul_f32_e32 v76, v80, v76
	v_cvt_pk_bf16_f32 v76, v76, s0
	ds_write_b16 v167, v76 offset:128
	v_mul_f32_e32 v76, v84, v138
	v_exp_f32_e32 v76, v76
	s_nop 0
	v_mul_f32_e32 v76, v76, v77
	v_cvt_pk_bf16_f32 v76, v76, s0
	ds_write_b16 v167, v76 offset:400
	v_mul_f32_e32 v76, v84, v139
	v_exp_f32_e32 v76, v76
	s_nop 0
	v_mul_f32_e32 v76, v76, v78
	v_cvt_pk_bf16_f32 v76, v76, s0
	ds_write_b16 v167, v76 offset:672
	v_mul_f32_e32 v76, v84, v140
	v_exp_f32_e32 v76, v76
	s_nop 0
	v_mul_f32_e32 v76, v76, v79
	v_cvt_pk_bf16_f32 v76, v76, s0
	ds_write_b16 v167, v76 offset:944
	ds_read_b128 v[76:79], v163 offset:29952
	ds_read_b128 v[80:83], v163 offset:30016
	s_waitcnt lgkmcnt(1)
	v_mfma_f32_16x16x32_bf16 v[76:79], v[72:75], v[76:79], 0
	s_waitcnt lgkmcnt(0)
	v_mfma_f32_16x16x32_bf16 v[76:79], v[68:71], v[80:83], v[76:79]
	v_mul_f32_e32 v80, v84, v141
	v_exp_f32_e32 v80, v80
	s_nop 5
	v_mul_f32_e32 v76, v80, v76
	v_cvt_pk_bf16_f32 v76, v76, s0
	ds_write_b16 v167, v76 offset:160
	v_mul_f32_e32 v76, v84, v142
	v_exp_f32_e32 v76, v76
	s_nop 0
	v_mul_f32_e32 v76, v76, v77
	v_cvt_pk_bf16_f32 v76, v76, s0
	ds_write_b16 v167, v76 offset:432
	v_mul_f32_e32 v76, v84, v143
	v_exp_f32_e32 v76, v76
	s_nop 0
	v_mul_f32_e32 v76, v76, v78
	v_cvt_pk_bf16_f32 v76, v76, s0
	ds_write_b16 v167, v76 offset:704
	v_mul_f32_e32 v76, v84, v144
	v_exp_f32_e32 v76, v76
	s_nop 0
	v_mul_f32_e32 v76, v76, v79
	v_cvt_pk_bf16_f32 v76, v76, s0
	ds_write_b16 v167, v76 offset:976
	ds_read_b128 v[76:79], v163 offset:32256
	ds_read_b128 v[80:83], v163 offset:32320
	s_waitcnt lgkmcnt(1)
	v_mfma_f32_16x16x32_bf16 v[76:79], v[72:75], v[76:79], 0
	s_waitcnt lgkmcnt(0)
	v_mfma_f32_16x16x32_bf16 v[76:79], v[68:71], v[80:83], v[76:79]
	v_mul_f32_e32 v80, v84, v145
	v_exp_f32_e32 v80, v80
	s_nop 5
	v_mul_f32_e32 v76, v80, v76
	v_cvt_pk_bf16_f32 v76, v76, s0
	ds_write_b16 v167, v76 offset:192
	v_mul_f32_e32 v76, v84, v146
	v_exp_f32_e32 v76, v76
	s_nop 0
	v_mul_f32_e32 v76, v76, v77
	v_cvt_pk_bf16_f32 v76, v76, s0
	ds_write_b16 v167, v76 offset:464
	v_mul_f32_e32 v76, v84, v147
	v_exp_f32_e32 v76, v76
	s_nop 0
	v_mul_f32_e32 v76, v76, v78
	v_cvt_pk_bf16_f32 v76, v76, s0
	ds_write_b16 v167, v76 offset:736
	v_mul_f32_e32 v76, v84, v148
	v_exp_f32_e32 v76, v76
	s_nop 0
	v_mul_f32_e32 v76, v76, v79
	v_cvt_pk_bf16_f32 v76, v76, s0
	ds_write_b16 v167, v76 offset:1008
	ds_read_b128 v[76:79], v163 offset:34560
	ds_read_b128 v[80:83], v163 offset:34624
	s_waitcnt lgkmcnt(1)
	v_mfma_f32_16x16x32_bf16 v[76:79], v[72:75], v[76:79], 0
	s_waitcnt lgkmcnt(0)
	v_mfma_f32_16x16x32_bf16 v[76:79], v[68:71], v[80:83], v[76:79]
	v_mul_f32_e32 v80, v84, v149
	v_exp_f32_e32 v80, v80
	s_nop 5
	v_mul_f32_e32 v76, v80, v76
	v_cvt_pk_bf16_f32 v76, v76, s0
	ds_write_b16 v167, v76 offset:224
	v_mul_f32_e32 v76, v84, v150
	v_exp_f32_e32 v76, v76
	s_nop 0
	v_mul_f32_e32 v76, v76, v77
	v_cvt_pk_bf16_f32 v76, v76, s0
	ds_write_b16 v167, v76 offset:496
	v_mul_f32_e32 v76, v84, v151
	v_exp_f32_e32 v76, v76
	s_nop 0
	v_mul_f32_e32 v76, v76, v78
	v_cvt_pk_bf16_f32 v76, v76, s0
	ds_write_b16 v167, v76 offset:768
	v_mul_f32_e32 v76, v84, v152
	v_exp_f32_e32 v76, v76
	s_nop 0
	v_mul_f32_e32 v76, v76, v79
	v_cvt_pk_bf16_f32 v76, v76, s0
	ds_write_b16 v167, v76 offset:1040
	v_mul_f32_e32 v76, v84, v153
	v_exp_f32_e32 v112, v76
	v_mul_f32_e32 v76, v84, v154
	v_exp_f32_e32 v110, v76
	v_mul_f32_e32 v76, v84, v155
	v_exp_f32_e32 v113, v76
	v_mul_f32_e32 v76, v84, v156
	v_exp_f32_e32 v111, v76
	v_mul_f32_e32 v76, v84, v157
	v_exp_f32_e32 v116, v76
	v_mul_f32_e32 v76, v84, v158
	v_exp_f32_e32 v114, v76
	v_mul_f32_e32 v76, v84, v159
	s_waitcnt lgkmcnt(0)
; #define LAS __attribute__((address_space(3)))
; #define MFMA16(a, b, c) __builtin_amdgcn_mfma_f32_16x16x32_bf16((a), (b), (c), 0, 0, 0)
; __device__ __forceinline__ void ret_out_phase(int l, LAS unsigned char* lds, int wave, int lane_) {
;     ...
;         for (int i = 0; i < 4; ++i) { const int nl = 16 * wave + 4 * fq + i; xfv[i] = __builtin_amdgcn_exp2f(l2g * (float)(nl + 1)); xbv[i] = __builtin_amdgcn_exp2f(l2g * (float)(RC - nl)); }
;         bf16x8 ap[4];
; #pragma unroll
;         for (int ks = 0; ks < 4; ++ks) ap[ks] = *(const LAS bf16x8*)(Pw + fr * KP + 32 * ks + 8 * fq);
; #pragma unroll
;         for (int g = 0; g < 2; ++g) {
;             if (g == 1) { RET_LD_STATES(1); }
; #pragma unroll
;             for (int o4 = 0; o4 < 4; ++o4) {
;                 const int ob = 4 * g + o4;
;                 f32x4 y2 = {0.f, 0.f, 0.f, 0.f}, y3 = y2; y1[ob] = y2;
; #pragma unroll
;                 for (int ks = 0; ks < 4; ++ks) { const bf16x8 bvv = *(const LAS bf16x8*)(Vt + (ob * 16 + fr) * KP + 32 * ks + 8 * fq); y1[ob] = MFMA16(ap[ks], bvv, y1[ob]); }
; #pragma unroll
;                 for (int ks = 0; ks < 2; ++ks) { y2 = MFMA16(aq[ks], __builtin_bit_cast(bf16x8, sfv[o4][ks]), y2); y3 = MFMA16(aq[ks], __builtin_bit_cast(bf16x8, sbv[o4][ks]), y3); }
;                 y1[ob] = y1[ob] + xfv * y2 + xbv * y3;
;             }
	v_exp_f32_e32 v117, v76
	v_mul_f32_e32 v76, v84, v160
	v_exp_f32_e32 v115, v76
	v_add_u32_e32 v76, v120, v93
	ds_read_b128 v[88:91], v76
	ds_read_b128 v[84:87], v76 offset:64
	ds_read_b128 v[80:83], v76 offset:128
	ds_read_b128 v[76:79], v76 offset:192
	ds_read_b128 v[182:185], v168 offset:36864
	ds_read_b128 v[186:189], v168 offset:36928
	s_waitcnt lgkmcnt(1)
	v_mfma_f32_16x16x32_bf16 v[182:185], v[88:91], v[182:185], 0
	s_waitcnt lgkmcnt(0)
	v_mfma_f32_16x16x32_bf16 v[182:185], v[84:87], v[186:189], v[182:185]
	ds_read_b128 v[186:189], v168 offset:36992
	s_waitcnt lgkmcnt(0)
	v_mfma_f32_16x16x32_bf16 v[182:185], v[80:83], v[186:189], v[182:185]
	ds_read_b128 v[186:189], v168 offset:37056
	s_waitcnt lgkmcnt(0)
	v_mfma_f32_16x16x32_bf16 v[182:185], v[76:79], v[186:189], v[182:185]
	s_nop 7
	v_pk_fma_f32 v[6:7], v[116:117], v[6:7], v[184:185]
	v_pk_fma_f32 v[4:5], v[112:113], v[4:5], v[182:183]
	v_pk_fma_f32 v[8:9], v[114:115], v[18:19], v[6:7]
	v_pk_fma_f32 v[24:25], v[110:111], v[16:17], v[4:5]
	ds_read_b128 v[4:7], v180 offset:36864
	ds_read_b128 v[16:19], v180 offset:36928
	s_waitcnt lgkmcnt(1)
	v_mfma_f32_16x16x32_bf16 v[4:7], v[88:91], v[4:7], 0
	s_waitcnt lgkmcnt(0)
	v_mfma_f32_16x16x32_bf16 v[4:7], v[84:87], v[16:19], v[4:7]
	ds_read_b128 v[16:19], v180 offset:36992
	s_waitcnt lgkmcnt(0)
	v_mfma_f32_16x16x32_bf16 v[4:7], v[80:83], v[16:19], v[4:7]
	ds_read_b128 v[16:19], v180 offset:37056
	s_waitcnt lgkmcnt(0)
	v_mfma_f32_16x16x32_bf16 v[4:7], v[76:79], v[16:19], v[4:7]
	v_mfma_f32_16x16x32_bf16 v[14:17], v[72:75], v[20:23], 0
	s_nop 6
	v_fma_f32 v6, v116, v12, v6
	v_fma_f32 v7, v117, v13, v7
	v_pk_fma_f32 v[4:5], v[112:113], v[10:11], v[4:5]
	v_mfma_f32_16x16x32_bf16 v[14:17], v[68:71], v[40:43], v[14:17]
	s_nop 7
	v_pk_fma_f32 v[10:11], v[114:115], v[16:17], v[6:7]
	v_pk_fma_f32 v[22:23], v[110:111], v[14:15], v[4:5]
	ds_read_b128 v[4:7], v180 offset:41216
	ds_read_b128 v[12:15], v180 offset:41280
	s_waitcnt lgkmcnt(1)
	v_mfma_f32_16x16x32_bf16 v[4:7], v[88:91], v[4:7], 0
	s_waitcnt lgkmcnt(0)
	v_mfma_f32_16x16x32_bf16 v[4:7], v[84:87], v[12:15], v[4:7]
	ds_read_b128 v[12:15], v180 offset:41344
	s_waitcnt lgkmcnt(0)
	v_mfma_f32_16x16x32_bf16 v[4:7], v[80:83], v[12:15], v[4:7]
	ds_read_b128 v[12:15], v180 offset:41408
	s_waitcnt lgkmcnt(0)
	v_mfma_f32_16x16x32_bf16 v[4:7], v[76:79], v[12:15], v[4:7]
	v_mfma_f32_16x16x32_bf16 v[12:15], v[72:75], v[28:31], 0
	v_mfma_f32_16x16x32_bf16 v[16:19], v[72:75], v[36:39], 0
	v_mfma_f32_16x16x32_bf16 v[12:15], v[68:71], v[48:51], v[12:15]
	v_mfma_f32_16x16x32_bf16 v[16:19], v[68:71], v[56:59], v[16:19]
	s_nop 6
	v_fma_f32 v6, v116, v14, v6
	v_fma_f32 v7, v117, v15, v7
	v_pk_fma_f32 v[4:5], v[112:113], v[12:13], v[4:5]
	v_pk_fma_f32 v[12:13], v[114:115], v[18:19], v[6:7]
	v_pk_fma_f32 v[26:27], v[110:111], v[16:17], v[4:5]
	ds_read_b128 v[4:7], v180 offset:45568
	ds_read_b128 v[14:17], v180 offset:45632
	s_waitcnt lgkmcnt(1)
	v_mfma_f32_16x16x32_bf16 v[4:7], v[88:91], v[4:7], 0
	s_waitcnt lgkmcnt(0)
	v_mfma_f32_16x16x32_bf16 v[4:7], v[84:87], v[14:17], v[4:7]
	ds_read_b128 v[14:17], v180 offset:45696
	s_waitcnt lgkmcnt(0)
	v_mfma_f32_16x16x32_bf16 v[4:7], v[80:83], v[14:17], v[4:7]
	ds_read_b128 v[14:17], v180 offset:45760
	s_waitcnt lgkmcnt(0)
	v_mfma_f32_16x16x32_bf16 v[4:7], v[76:79], v[14:17], v[4:7]
	v_mfma_f32_16x16x32_bf16 v[14:17], v[72:75], v[44:47], 0
	v_mfma_f32_16x16x32_bf16 v[18:21], v[72:75], v[52:55], 0
	v_mfma_f32_16x16x32_bf16 v[14:17], v[68:71], v[60:63], v[14:17]
	v_mfma_f32_16x16x32_bf16 v[18:21], v[68:71], v[64:67], v[18:21]
	s_nop 6
	v_fma_f32 v6, v116, v16, v6
	v_fma_f32 v7, v117, v17, v7
	v_pk_fma_f32 v[4:5], v[112:113], v[14:15], v[4:5]
	v_add_u32_e32 v16, 0xffffc000, v161
	v_pk_fma_f32 v[14:15], v[114:115], v[20:21], v[6:7]
	v_pk_fma_f32 v[28:29], v[110:111], v[18:19], v[4:5]
	buffer_load_dwordx4 v[4:7], v161, s[60:63], 0 offen sc0 sc1
	buffer_load_dwordx4 v[38:41], v16, s[60:63], 0 offen sc0 sc1
	v_add_u32_e32 v16, 0xffffbfc0, v161
	v_subrev_u32_e32 v17, 64, v161
	buffer_load_dwordx4 v[42:45], v17, s[60:63], 0 offen sc0 sc1
	buffer_load_dwordx4 v[46:49], v16, s[60:63], 0 offen sc0 sc1
	v_add_u32_e32 v16, 0xfffff800, v161
	buffer_load_dwordx4 v[50:53], v16, s[60:63], 0 offen sc0 sc1
	v_add_u32_e32 v16, 0xffffb800, v161
	buffer_load_dwordx4 v[54:57], v16, s[60:63], 0 offen sc0 sc1
	v_add_u32_e32 v16, 0xffffb7c0, v161
	v_add_u32_e32 v17, 0xfffff7c0, v161
	buffer_load_dwordx4 v[58:61], v17, s[60:63], 0 offen sc0 sc1
	buffer_load_dwordx4 v[62:65], v16, s[60:63], 0 offen sc0 sc1
	v_add_u32_e32 v16, 0xfffff000, v161
	buffer_load_dwordx4 v[18:21], v16, s[60:63], 0 offen sc0 sc1
	v_add_u32_e32 v16, 0xffffb000, v161
	buffer_load_dwordx4 v[34:37], v16, s[60:63], 0 offen sc0 sc1
	v_add_u32_e32 v16, 0xffffafc0, v161
	v_add_u32_e32 v17, 0xffffefc0, v161
	buffer_load_dwordx4 v[182:185], v17, s[60:63], 0 offen sc0 sc1
	buffer_load_dwordx4 v[186:189], v16, s[60:63], 0 offen sc0 sc1
	v_add_u32_e32 v16, 0xffffe800, v161
	buffer_load_dwordx4 v[30:33], v16, s[60:63], 0 offen sc0 sc1
	v_add_u32_e32 v16, 0xffffa800, v161
	buffer_load_dwordx4 v[190:193], v16, s[60:63], 0 offen sc0 sc1
	v_add_u32_e32 v16, 0xffffe7c0, v161
	buffer_load_dwordx4 v[194:197], v16, s[60:63], 0 offen sc0 sc1
	buffer_load_dwordx4 v[208:211], v109, s[60:63], 0 offen sc0 sc1
	ds_read_b128 v[212:215], v180 offset:49920
	ds_read_b128 v[216:219], v180 offset:49984
	s_waitcnt lgkmcnt(1)
	v_mfma_f32_16x16x32_bf16 v[212:215], v[88:91], v[212:215], 0
	v_add_u32_e32 v161, s27, v161
	s_waitcnt lgkmcnt(0)
	v_mfma_f32_16x16x32_bf16 v[212:215], v[84:87], v[216:219], v[212:215]
	ds_read_b128 v[216:219], v180 offset:50048
	s_waitcnt vmcnt(1)
; #define LAS __attribute__((address_space(3)))
; #define MFMA16(a, b, c) __builtin_amdgcn_mfma_f32_16x16x32_bf16((a), (b), (c), 0, 0, 0)
; __device__ __forceinline__ void ret_out_phase(int l, LAS unsigned char* lds, int wave, int lane_) {
;     ...
;         for (int g = 0; g < 2; ++g) {
;             if (g == 1) { RET_LD_STATES(1); }
; #pragma unroll
;             for (int o4 = 0; o4 < 4; ++o4) {
;                 const int ob = 4 * g + o4;
;                 f32x4 y2 = {0.f, 0.f, 0.f, 0.f}, y3 = y2; y1[ob] = y2;
; #pragma unroll
;                 for (int ks = 0; ks < 4; ++ks) { const bf16x8 bvv = *(const LAS bf16x8*)(Vt + (ob * 16 + fr) * KP + 32 * ks + 8 * fq); y1[ob] = MFMA16(ap[ks], bvv, y1[ob]); }
; #pragma unroll
;                 for (int ks = 0; ks < 2; ++ks) { y2 = MFMA16(aq[ks], __builtin_bit_cast(bf16x8, sfv[o4][ks]), y2); y3 = MFMA16(aq[ks], __builtin_bit_cast(bf16x8, sbv[o4][ks]), y3); }
;                 y1[ob] = y1[ob] + xfv * y2 + xbv * y3;
;             }
;             asm volatile("" ::: "memory");
;         }
; #pragma unroll
;         for (int i = 0; i < 4; ++i) {
;             const int nl = 16 * wave + 4 * fq + i;
;             float v[8]; float s = 0.f;
; #pragma unroll
;             for (int ob = 0; ob < 8; ++ob) { v[ob] = y1[ob][i]; s += v[ob]; }
;             s += __shfl_xor(s, 1); s += __shfl_xor(s, 2); s += __shfl_xor(s, 4); s += __shfl_xor(s, 8);
;             const float mean = s * (1.f / 128.f); float q = 0.f;
; #pragma unroll
;             for (int ob = 0; ob < 8; ++ob) { v[ob] -= mean; q += v[ob] * v[ob]; }
;             q += __shfl_xor(q, 1); q += __shfl_xor(q, 2); q += __shfl_xor(q, 4); q += __shfl_xor(q, 8);
	v_mfma_f32_16x16x32_bf16 v[194:197], v[72:75], v[194:197], 0
	v_mfma_f32_16x16x32_bf16 v[30:33], v[68:71], v[30:33], v[194:197]
	s_nop 6
	ds_read_b128 v[194:197], v180 offset:54336
	s_waitcnt lgkmcnt(1)
	v_mfma_f32_16x16x32_bf16 v[212:215], v[80:83], v[216:219], v[212:215]
	ds_read_b128 v[216:219], v180 offset:50112
	s_waitcnt vmcnt(0)
	v_mfma_f32_16x16x32_bf16 v[208:211], v[72:75], v[208:211], 0
	v_mfma_f32_16x16x32_bf16 v[186:189], v[72:75], v[186:189], 0
	v_mfma_f32_16x16x32_bf16 v[190:193], v[68:71], v[190:193], v[208:211]
	v_mfma_f32_16x16x32_bf16 v[34:37], v[68:71], v[34:37], v[186:189]
	s_nop 5
	ds_read_b128 v[186:189], v180 offset:58688
	s_waitcnt lgkmcnt(1)
	v_mfma_f32_16x16x32_bf16 v[212:215], v[76:79], v[216:219], v[212:215]
	v_mfma_f32_16x16x32_bf16 v[182:185], v[72:75], v[182:185], 0
	v_mfma_f32_16x16x32_bf16 v[182:185], v[68:71], v[18:21], v[182:185]
	s_nop 5
	v_fma_f32 v16, v116, v192, v214
	v_fma_f32 v17, v117, v193, v215
	v_pk_fma_f32 v[66:67], v[112:113], v[190:191], v[212:213]
	ds_read_b128 v[190:193], v180 offset:54272
	s_waitcnt lgkmcnt(0)
	v_mfma_f32_16x16x32_bf16 v[190:193], v[88:91], v[190:193], 0
	v_fma_f32 v16, v114, v32, v16
	v_fma_f32 v17, v115, v33, v17
	v_pk_fma_f32 v[32:33], v[110:111], v[30:31], v[66:67]
	v_mfma_f32_16x16x32_bf16 v[190:193], v[84:87], v[194:197], v[190:193]
	ds_read_b128 v[194:197], v180 offset:54400
	s_waitcnt lgkmcnt(0)
	v_mfma_f32_16x16x32_bf16 v[190:193], v[80:83], v[194:197], v[190:193]
	ds_read_b128 v[194:197], v180 offset:54464
	s_waitcnt lgkmcnt(0)
	v_mfma_f32_16x16x32_bf16 v[190:193], v[76:79], v[194:197], v[190:193]
	v_mfma_f32_16x16x32_bf16 v[62:65], v[72:75], v[62:65], 0
	s_nop 6
	v_fma_f32 v18, v116, v36, v192
	v_fma_f32 v19, v117, v37, v193
	v_pk_fma_f32 v[20:21], v[112:113], v[34:35], v[190:191]
	v_pk_fma_f32 v[18:19], v[114:115], v[184:185], v[18:19]
	v_pk_fma_f32 v[34:35], v[110:111], v[182:183], v[20:21]
	ds_read_b128 v[182:185], v180 offset:58624
	s_waitcnt lgkmcnt(0)
	v_mfma_f32_16x16x32_bf16 v[182:185], v[88:91], v[182:185], 0
	v_mfma_f32_16x16x32_bf16 v[182:185], v[84:87], v[186:189], v[182:185]
	ds_read_b128 v[186:189], v180 offset:58752
	s_waitcnt lgkmcnt(0)
	v_mfma_f32_16x16x32_bf16 v[182:185], v[80:83], v[186:189], v[182:185]
	ds_read_b128 v[186:189], v180 offset:58816
	v_mfma_f32_16x16x32_bf16 v[58:61], v[72:75], v[58:61], 0
	s_waitcnt lgkmcnt(0)
	v_mfma_f32_16x16x32_bf16 v[182:185], v[76:79], v[186:189], v[182:185]
	v_mfma_f32_16x16x32_bf16 v[54:57], v[68:71], v[54:57], v[62:65]
	v_mfma_f32_16x16x32_bf16 v[50:53], v[68:71], v[50:53], v[58:61]
	v_mfma_f32_16x16x32_bf16 v[46:49], v[72:75], v[46:49], 0
	s_nop 5
	v_fma_f32 v20, v116, v56, v184
	v_fma_f32 v21, v117, v57, v185
	v_pk_fma_f32 v[30:31], v[112:113], v[54:55], v[182:183]
	v_pk_fma_f32 v[20:21], v[114:115], v[52:53], v[20:21]
	v_pk_fma_f32 v[36:37], v[110:111], v[50:51], v[30:31]
	ds_read_b128 v[50:53], v180 offset:62976
	ds_read_b128 v[54:57], v180 offset:63040
	s_waitcnt lgkmcnt(1)
	v_mfma_f32_16x16x32_bf16 v[50:53], v[88:91], v[50:53], 0
	v_mov_b32_e32 v61, v36
	s_waitcnt lgkmcnt(0)
	v_mfma_f32_16x16x32_bf16 v[50:53], v[84:87], v[54:57], v[50:53]
	ds_read_b128 v[54:57], v180 offset:63104
	s_waitcnt lgkmcnt(0)
	v_mfma_f32_16x16x32_bf16 v[50:53], v[80:83], v[54:57], v[50:53]
	ds_read_b128 v[54:57], v180 offset:63168
	s_load_dwordx2 s[48:49], s[30:31], 0x90
	v_mfma_f32_16x16x32_bf16 v[42:45], v[72:75], v[42:45], 0
	s_waitcnt lgkmcnt(0)
	s_add_u32 s43, s48, s26
	v_mfma_f32_16x16x32_bf16 v[50:53], v[76:79], v[54:57], v[50:53]
	s_addc_u32 s47, s49, 0
	s_lshl_b32 s42, s42, 9
	s_add_u32 s42, s43, s42
	v_mfma_f32_16x16x32_bf16 v[38:41], v[68:71], v[38:41], v[46:49]
	s_addc_u32 s43, s47, 0
	s_add_i32 s46, s46, s58
	s_add_i32 s29, s29, s28
	v_mfma_f32_16x16x32_bf16 v[4:7], v[68:71], v[4:7], v[42:45]
	s_cmpk_lt_i32 s46, 0x800
	s_nop 2
	v_pk_fma_f32 v[30:31], v[116:117], v[40:41], v[52:53]
	v_pk_fma_f32 v[38:39], v[112:113], v[38:39], v[50:51]
	v_lshlrev_b32_e32 v44, 2, v92
	global_load_dword v55, v44, s[42:43]
	global_load_dword v54, v44, s[42:43] offset:64
	global_load_dword v53, v44, s[42:43] offset:128
	global_load_dword v52, v44, s[42:43] offset:192
	global_load_dword v51, v44, s[42:43] offset:256
	global_load_dword v50, v44, s[42:43] offset:320
	global_load_dword v49, v44, s[42:43] offset:384
	global_load_dword v48, v44, s[42:43] offset:448
	v_pk_add_f32 v[44:45], v[24:25], 0 op_sel_hi:[1,0]
	v_pk_fma_f32 v[38:39], v[110:111], v[4:5], v[38:39]
	v_pk_add_f32 v[44:45], v[44:45], v[22:23]
	v_and_b32_e32 v5, 64, v198
	v_pk_add_f32 v[44:45], v[44:45], v[26:27]
	v_xor_b32_e32 v4, 1, v198
	v_pk_add_f32 v[44:45], v[44:45], v[28:29]
	v_add_u32_e32 v5, 64, v5
	v_pk_add_f32 v[44:45], v[44:45], v[32:33]
	v_cmp_lt_i32_e32 vcc, v4, v5
	v_pk_add_f32 v[44:45], v[44:45], v[34:35]
	v_pk_fma_f32 v[6:7], v[114:115], v[6:7], v[30:31]
	v_cndmask_b32_e32 v4, v198, v4, vcc
	v_mov_b32_e32 v30, v28
	v_mov_b32_e32 v31, v26
	v_mov_b32_e32 v26, v29
	v_pk_add_f32 v[28:29], v[44:45], v[36:37]
	v_lshlrev_b32_e32 v56, 2, v4
	v_pk_add_f32 v[28:29], v[28:29], v[38:39]
	ds_bpermute_b32 v44, v56, v28
	ds_bpermute_b32 v45, v56, v29
	v_xor_b32_e32 v4, 2, v198
	v_cmp_lt_i32_e32 vcc, v4, v5
	v_mov_b32_e32 v42, v34
	v_mov_b32_e32 v43, v32
	v_cndmask_b32_e32 v4, v198, v4, vcc
	v_lshlrev_b32_e32 v57, 2, v4
	s_waitcnt lgkmcnt(0)
	v_pk_add_f32 v[28:29], v[28:29], v[44:45]
	ds_bpermute_b32 v44, v57, v28
	ds_bpermute_b32 v45, v57, v29
	v_xor_b32_e32 v4, 4, v198
	v_cmp_lt_i32_e32 vcc, v4, v5
	v_mov_b32_e32 v32, v35
	v_mov_b32_e32 v36, v39
	v_cndmask_b32_e32 v4, v198, v4, vcc
	v_lshlrev_b32_e32 v58, 2, v4
	s_waitcnt lgkmcnt(0)
; __device__ __forceinline__ unsigned f2bf(float f) { return cvtpk(f, 0.f) & 0xffffu; }
; __device__ __forceinline__ void ret_out_phase(int l, LAS unsigned char* lds, int wave, int lane_) {
;     ...
;         for (int i = 0; i < 4; ++i) {
;             const int nl = 16 * wave + 4 * fq + i;
;             float v[8]; float s = 0.f;
; #pragma unroll
;             for (int ob = 0; ob < 8; ++ob) { v[ob] = y1[ob][i]; s += v[ob]; }
;             s += __shfl_xor(s, 1); s += __shfl_xor(s, 2); s += __shfl_xor(s, 4); s += __shfl_xor(s, 8);
;             const float mean = s * (1.f / 128.f); float q = 0.f;
; #pragma unroll
;             for (int ob = 0; ob < 8; ++ob) { v[ob] -= mean; q += v[ob] * v[ob]; }
;             q += __shfl_xor(q, 1); q += __shfl_xor(q, 2); q += __shfl_xor(q, 4); q += __shfl_xor(q, 8);
;             const float rstd = rsqrtf(q * (1.f / 128.f) + 1e-6f);
;             bf16* yo = (bf16*)(ws + OFF_YB) + ((size_t)b * SEQ + j * RC + nl) * DM + h * 128;
;             const float* gn = p->in[I_RG] + (size_t)l * DM + h * 128;
; #pragma unroll
;             for (int ob = 0; ob < 8; ++ob) yo[ob * 16 + fr] = (bf16)f2bf(v[ob] * rstd * gn[ob * 16 + fr]);
	v_pk_add_f32 v[28:29], v[28:29], v[44:45]
	ds_bpermute_b32 v44, v58, v28
	ds_bpermute_b32 v45, v58, v29
	v_xor_b32_e32 v4, 8, v198
	v_cmp_lt_i32_e32 vcc, v4, v5
	v_mov_b32_e32 v60, v38
	s_mov_b32 s42, 0x358637bd
	v_cndmask_b32_e32 v4, v198, v4, vcc
	v_lshlrev_b32_e32 v59, 2, v4
	s_waitcnt lgkmcnt(0)
	v_pk_add_f32 v[28:29], v[28:29], v[44:45]
	ds_bpermute_b32 v44, v59, v28
	ds_bpermute_b32 v45, v59, v29
	v_lshl_add_u64 v[4:5], s[34:35], 0, v[100:101]
	v_lshlrev_b64 v[4:5], 11, v[4:5]
	v_lshl_add_u64 v[40:41], s[36:37], 0, v[4:5]
	v_lshlrev_b32_e32 v4, 1, v92
	s_waitcnt lgkmcnt(0)
	v_pk_add_f32 v[28:29], v[28:29], v[44:45]
	v_mov_b32_e32 v5, v3
	v_pk_mul_f32 v[62:63], v[28:29], s[86:87] op_sel_hi:[1,0]
	v_lshl_add_u64 v[40:41], v[40:41], 0, v[4:5]
	v_pk_add_f32 v[46:47], v[30:31], v[62:63] op_sel_hi:[1,0] neg_lo:[0,1] neg_hi:[0,1]
	v_pk_fma_f32 v[30:31], v[28:29], s[86:87], v[24:25] op_sel_hi:[1,0,1] neg_lo:[1,0,0] neg_hi:[1,0,0]
	v_pk_fma_f32 v[28:29], v[28:29], s[86:87], v[22:23] op_sel_hi:[1,0,1] neg_lo:[1,0,0] neg_hi:[1,0,0]
	v_pk_add_f32 v[26:27], v[26:27], v[62:63] op_sel:[0,1] neg_lo:[0,1] neg_hi:[0,1]
	v_pk_mul_f32 v[64:65], v[46:47], v[46:47]
	v_pk_mul_f32 v[22:23], v[28:29], v[28:29]
	v_pk_mul_f32 v[70:71], v[26:27], v[26:27]
	v_pk_add_f32 v[44:45], v[42:43], v[62:63] op_sel_hi:[1,0] neg_lo:[0,1] neg_hi:[0,1]
	v_pk_fma_f32 v[68:69], v[30:31], v[30:31], v[22:23]
	v_pk_add_f32 v[24:25], v[32:33], v[62:63] op_sel:[0,1] neg_lo:[0,1] neg_hi:[0,1]
	v_pk_add_f32 v[22:23], v[36:37], v[62:63] op_sel:[0,1] neg_lo:[0,1] neg_hi:[0,1]
	v_mov_b32_e32 v37, v64
	v_mov_b32_e32 v64, v71
	v_pk_mul_f32 v[66:67], v[44:45], v[44:45]
	v_pk_mul_f32 v[32:33], v[24:25], v[24:25]
	v_mov_b32_e32 v36, v70
	v_pk_add_f32 v[38:39], v[64:65], v[68:69] op_sel:[0,1] op_sel_hi:[1,0]
	v_pk_add_f32 v[42:43], v[60:61], v[62:63] op_sel_hi:[1,0] neg_lo:[0,1] neg_hi:[0,1]
	v_pk_add_f32 v[36:37], v[36:37], v[38:39]
	v_mov_b32_e32 v38, v33
	v_mov_b32_e32 v39, v67
	v_pk_mul_f32 v[60:61], v[42:43], v[42:43]
	v_pk_mul_f32 v[34:35], v[22:23], v[22:23]
	v_pk_add_f32 v[36:37], v[38:39], v[36:37]
	v_mov_b32_e32 v33, v66
	v_pk_add_f32 v[32:33], v[32:33], v[36:37]
	v_mov_b32_e32 v36, v35
	v_mov_b32_e32 v37, v61
	v_pk_add_f32 v[32:33], v[36:37], v[32:33]
	v_mov_b32_e32 v35, v60
	v_pk_add_f32 v[32:33], v[34:35], v[32:33]
	ds_bpermute_b32 v35, v56, v33
	ds_bpermute_b32 v34, v56, v32
	s_waitcnt lgkmcnt(0)
	v_pk_add_f32 v[32:33], v[32:33], v[34:35]
	ds_bpermute_b32 v35, v57, v33
	ds_bpermute_b32 v34, v57, v32
	s_waitcnt lgkmcnt(0)
	v_pk_add_f32 v[32:33], v[32:33], v[34:35]
	ds_bpermute_b32 v35, v58, v33
	ds_bpermute_b32 v34, v58, v32
	s_waitcnt lgkmcnt(0)
	v_pk_add_f32 v[32:33], v[32:33], v[34:35]
	ds_bpermute_b32 v35, v59, v33
	ds_bpermute_b32 v34, v59, v32
	s_waitcnt lgkmcnt(0)
	v_pk_add_f32 v[34:35], v[32:33], v[34:35]
	v_mov_b64_e32 v[32:33], s[42:43]
	v_pk_fma_f32 v[34:35], v[34:35], s[86:87], v[32:33] op_sel_hi:[1,0,0]
	s_nop 0
	v_mul_f32_e32 v36, 0x4b800000, v35
	v_cmp_gt_f32_e64 s[42:43], s19, v35
	v_cmp_gt_f32_e32 vcc, s19, v34
	s_nop 0
	v_cndmask_b32_e64 v35, v35, v36, s[42:43]
	v_rsq_f32_e32 v35, v35
	s_nop 0
	v_mul_f32_e32 v36, 0x45800000, v35
	v_cndmask_b32_e64 v35, v35, v36, s[42:43]
	v_mul_f32_e32 v28, v28, v35
	s_waitcnt vmcnt(6)
	v_mul_f32_e32 v28, v54, v28
	v_cvt_pk_bf16_f32 v28, v28, s0
	global_store_short v[40:41], v28, off offset:32
	v_mul_f32_e32 v28, v47, v35
	s_waitcnt vmcnt(6)
	v_mul_f32_e32 v28, v53, v28
	v_cvt_pk_bf16_f32 v28, v28, s0
	global_store_short v[40:41], v28, off offset:64
	v_mul_f32_e32 v28, v46, v35
	s_waitcnt vmcnt(6)
	v_mul_f32_e32 v28, v52, v28
	v_cvt_pk_bf16_f32 v28, v28, s0
	global_store_short v[40:41], v28, off offset:96
	v_mul_f32_e32 v28, v45, v35
	s_waitcnt vmcnt(6)
	v_mul_f32_e32 v28, v51, v28
	v_cvt_pk_bf16_f32 v28, v28, s0
	global_store_short v[40:41], v28, off offset:128
	v_mul_f32_e32 v28, v44, v35
	s_waitcnt vmcnt(6)
	v_mul_f32_e32 v28, v50, v28
	v_cvt_pk_bf16_f32 v28, v28, s0
	global_store_short v[40:41], v28, off offset:160
	v_mul_f32_e32 v28, v43, v35
	s_waitcnt vmcnt(6)
	v_mul_f32_e32 v28, v49, v28
	v_cvt_pk_bf16_f32 v28, v28, s0
	global_store_short v[40:41], v28, off offset:192
	v_mul_f32_e32 v28, v42, v35
	s_waitcnt vmcnt(6)
	v_mul_f32_e32 v28, v48, v28
	v_cvt_pk_bf16_f32 v28, v28, s0
	global_store_short v[40:41], v28, off offset:224
	v_mul_f32_e32 v28, 0x4b800000, v34
	v_cndmask_b32_e32 v28, v34, v28, vcc
	v_rsq_f32_e32 v28, v28
	v_mul_f32_e32 v30, v30, v35
	v_mul_f32_e32 v30, v55, v30
	v_cvt_pk_bf16_f32 v30, v30, s0
	global_store_short v[40:41], v30, off
	v_mul_f32_e32 v30, 0x45800000, v28
	v_cndmask_b32_e32 v28, v28, v30, vcc
	v_lshl_add_u64 v[34:35], s[34:35], 0, v[102:103]
	v_lshlrev_b64 v[34:35], 11, v[34:35]
	v_mul_f32_e32 v30, v31, v28
	v_mul_f32_e32 v29, v29, v28
	v_mul_f32_e32 v27, v27, v28
	v_mul_f32_e32 v26, v26, v28
	v_mul_f32_e32 v25, v25, v28
	v_mul_f32_e32 v24, v24, v28
	v_mul_f32_e32 v23, v23, v28
	v_mul_f32_e32 v22, v22, v28
	v_lshl_add_u64 v[34:35], s[36:37], 0, v[34:35]
	v_mul_f32_e32 v30, v55, v30
	v_mul_f32_e32 v29, v54, v29
	v_mul_f32_e32 v27, v53, v27
	v_mul_f32_e32 v26, v52, v26
	v_mul_f32_e32 v25, v51, v25
	v_mul_f32_e32 v24, v50, v24
	v_mul_f32_e32 v23, v49, v23
	v_mul_f32_e32 v22, v48, v22
	v_cvt_pk_bf16_f32 v36, v30, s0
	v_lshl_add_u64 v[30:31], v[34:35], 0, v[4:5]
	v_cvt_pk_bf16_f32 v29, v29, s0
	v_cvt_pk_bf16_f32 v27, v27, s0
	v_cvt_pk_bf16_f32 v26, v26, s0
	v_cvt_pk_bf16_f32 v25, v25, s0
	v_cvt_pk_bf16_f32 v24, v24, s0
	v_cvt_pk_bf16_f32 v23, v23, s0
	v_cvt_pk_bf16_f32 v22, v22, s0
	global_store_short v[30:31], v36, off
	global_store_short v[30:31], v29, off offset:32
	global_store_short v[30:31], v27, off offset:64
	global_store_short v[30:31], v26, off offset:96
	global_store_short v[30:31], v25, off offset:128
	global_store_short v[30:31], v24, off offset:160
	global_store_short v[30:31], v23, off offset:192
	global_store_short v[30:31], v22, off offset:224
	v_pk_add_f32 v[30:31], v[8:9], 0 op_sel_hi:[1,0]
	v_mov_b32_e32 v22, v14
	v_pk_add_f32 v[30:31], v[30:31], v[10:11]
	v_mov_b32_e32 v23, v12
	v_pk_add_f32 v[30:31], v[30:31], v[12:13]
	v_mov_b32_e32 v12, v15
	v_pk_add_f32 v[30:31], v[30:31], v[14:15]
	v_mov_b32_e32 v24, v18
	v_pk_add_f32 v[30:31], v[30:31], v[16:17]
	v_mov_b32_e32 v25, v16
	v_pk_add_f32 v[30:31], v[30:31], v[18:19]
	v_mov_b32_e32 v27, v20
	v_pk_add_f32 v[14:15], v[30:31], v[20:21]
	v_mov_b32_e32 v16, v19
	v_pk_add_f32 v[14:15], v[14:15], v[6:7]
	ds_bpermute_b32 v30, v56, v14
	ds_bpermute_b32 v31, v56, v15
	v_mov_b32_e32 v20, v7
	v_mov_b32_e32 v26, v6
	v_lshl_add_u64 v[28:29], s[34:35], 0, v[104:105]
	v_lshlrev_b64 v[28:29], 11, v[28:29]
	s_waitcnt lgkmcnt(0)
; __device__ __forceinline__ unsigned f2bf(float f) { return cvtpk(f, 0.f) & 0xffffu; }
; __device__ __forceinline__ void ret_out_phase(int l, LAS unsigned char* lds, int wave, int lane_) {
;     ...
;         for (int i = 0; i < 4; ++i) {
;             const int nl = 16 * wave + 4 * fq + i;
;             float v[8]; float s = 0.f;
; #pragma unroll
;             for (int ob = 0; ob < 8; ++ob) { v[ob] = y1[ob][i]; s += v[ob]; }
;             s += __shfl_xor(s, 1); s += __shfl_xor(s, 2); s += __shfl_xor(s, 4); s += __shfl_xor(s, 8);
;             const float mean = s * (1.f / 128.f); float q = 0.f;
; #pragma unroll
;             for (int ob = 0; ob < 8; ++ob) { v[ob] -= mean; q += v[ob] * v[ob]; }
;             q += __shfl_xor(q, 1); q += __shfl_xor(q, 2); q += __shfl_xor(q, 4); q += __shfl_xor(q, 8);
;             const float rstd = rsqrtf(q * (1.f / 128.f) + 1e-6f);
;             bf16* yo = (bf16*)(ws + OFF_YB) + ((size_t)b * SEQ + j * RC + nl) * DM + h * 128;
;             const float* gn = p->in[I_RG] + (size_t)l * DM + h * 128;
; #pragma unroll
;             for (int ob = 0; ob < 8; ++ob) yo[ob * 16 + fr] = (bf16)f2bf(v[ob] * rstd * gn[ob * 16 + fr]);
;         }
;         __syncthreads();
;     }
	v_pk_add_f32 v[14:15], v[14:15], v[30:31]
	ds_bpermute_b32 v30, v57, v14
	ds_bpermute_b32 v31, v57, v15
	v_lshl_add_u64 v[28:29], s[36:37], 0, v[28:29]
	v_lshl_add_u64 v[28:29], v[28:29], 0, v[4:5]
	s_waitcnt lgkmcnt(0)
	v_pk_add_f32 v[14:15], v[14:15], v[30:31]
	ds_bpermute_b32 v30, v58, v14
	ds_bpermute_b32 v31, v58, v15
	s_waitcnt lgkmcnt(0)
	v_pk_add_f32 v[14:15], v[14:15], v[30:31]
	ds_bpermute_b32 v30, v59, v14
	ds_bpermute_b32 v31, v59, v15
	s_waitcnt lgkmcnt(0)
	v_pk_add_f32 v[14:15], v[14:15], v[30:31]
	s_nop 0
	v_pk_mul_f32 v[30:31], v[14:15], s[86:87] op_sel_hi:[1,0]
	s_nop 0
	v_pk_add_f32 v[34:35], v[22:23], v[30:31] op_sel_hi:[1,0] neg_lo:[0,1] neg_hi:[0,1]
	v_pk_fma_f32 v[22:23], v[14:15], s[86:87], v[8:9] op_sel_hi:[1,0,1] neg_lo:[1,0,0] neg_hi:[1,0,0]
	v_pk_fma_f32 v[14:15], v[14:15], s[86:87], v[10:11] op_sel_hi:[1,0,1] neg_lo:[1,0,0] neg_hi:[1,0,0]
	v_pk_add_f32 v[10:11], v[12:13], v[30:31] op_sel:[0,1] neg_lo:[0,1] neg_hi:[0,1]
	v_pk_mul_f32 v[36:37], v[34:35], v[34:35]
	v_pk_mul_f32 v[8:9], v[14:15], v[14:15]
	v_pk_mul_f32 v[12:13], v[10:11], v[10:11]
	v_pk_add_f32 v[24:25], v[24:25], v[30:31] op_sel_hi:[1,0] neg_lo:[0,1] neg_hi:[0,1]
	v_pk_fma_f32 v[42:43], v[22:23], v[22:23], v[8:9]
	v_pk_add_f32 v[8:9], v[16:17], v[30:31] op_sel:[0,1] neg_lo:[0,1] neg_hi:[0,1]
	v_pk_add_f32 v[6:7], v[20:21], v[30:31] op_sel:[0,1] neg_lo:[0,1] neg_hi:[0,1]
	v_mov_b32_e32 v21, v36
	v_mov_b32_e32 v36, v13
	v_pk_mul_f32 v[38:39], v[24:25], v[24:25]
	v_pk_mul_f32 v[16:17], v[8:9], v[8:9]
	v_mov_b32_e32 v20, v12
	v_pk_add_f32 v[12:13], v[36:37], v[42:43] op_sel:[0,1] op_sel_hi:[1,0]
	v_pk_add_f32 v[26:27], v[26:27], v[30:31] op_sel_hi:[1,0] neg_lo:[0,1] neg_hi:[0,1]
	v_pk_add_f32 v[12:13], v[20:21], v[12:13]
	v_mov_b32_e32 v20, v17
	v_mov_b32_e32 v21, v39
	v_pk_mul_f32 v[40:41], v[26:27], v[26:27]
	v_pk_mul_f32 v[18:19], v[6:7], v[6:7]
	v_pk_add_f32 v[12:13], v[20:21], v[12:13]
	v_mov_b32_e32 v17, v38
	v_pk_add_f32 v[12:13], v[16:17], v[12:13]
	v_mov_b32_e32 v16, v19
	v_mov_b32_e32 v17, v41
	v_pk_add_f32 v[12:13], v[16:17], v[12:13]
	v_mov_b32_e32 v19, v40
	v_pk_add_f32 v[12:13], v[18:19], v[12:13]
	ds_bpermute_b32 v17, v56, v13
	ds_bpermute_b32 v16, v56, v12
	s_waitcnt lgkmcnt(0)
	v_pk_add_f32 v[12:13], v[12:13], v[16:17]
	ds_bpermute_b32 v17, v57, v13
	ds_bpermute_b32 v16, v57, v12
	s_waitcnt lgkmcnt(0)
	v_pk_add_f32 v[12:13], v[12:13], v[16:17]
	ds_bpermute_b32 v17, v58, v13
	ds_bpermute_b32 v16, v58, v12
	s_waitcnt lgkmcnt(0)
	v_pk_add_f32 v[12:13], v[12:13], v[16:17]
	ds_bpermute_b32 v17, v59, v13
	ds_bpermute_b32 v16, v59, v12
	s_waitcnt lgkmcnt(0)
	v_pk_add_f32 v[12:13], v[12:13], v[16:17]
	s_nop 0
	v_pk_fma_f32 v[12:13], v[12:13], s[86:87], v[32:33] op_sel_hi:[1,0,0]
	s_nop 0
	v_mul_f32_e32 v16, 0x4b800000, v13
	v_cmp_gt_f32_e64 s[42:43], s19, v13
	v_cmp_gt_f32_e32 vcc, s19, v12
	s_nop 0
	v_cndmask_b32_e64 v13, v13, v16, s[42:43]
	v_rsq_f32_e32 v13, v13
	s_nop 0
	v_mul_f32_e32 v16, 0x45800000, v13
	v_cndmask_b32_e64 v13, v13, v16, s[42:43]
	v_mul_f32_e32 v14, v14, v13
	v_mul_f32_e32 v14, v54, v14
	v_cvt_pk_bf16_f32 v14, v14, s0
	global_store_short v[28:29], v14, off offset:32
	v_mul_f32_e32 v14, v35, v13
	v_mul_f32_e32 v14, v53, v14
	v_cvt_pk_bf16_f32 v14, v14, s0
	global_store_short v[28:29], v14, off offset:64
	v_mul_f32_e32 v14, v34, v13
	v_mul_f32_e32 v14, v52, v14
	v_cvt_pk_bf16_f32 v14, v14, s0
	global_store_short v[28:29], v14, off offset:96
	v_mul_f32_e32 v14, v25, v13
	v_mul_f32_e32 v14, v51, v14
	v_cvt_pk_bf16_f32 v14, v14, s0
	global_store_short v[28:29], v14, off offset:128
	v_mul_f32_e32 v14, v24, v13
	v_mul_f32_e32 v14, v50, v14
	v_cvt_pk_bf16_f32 v14, v14, s0
	v_mul_f32_e32 v16, v22, v13
	global_store_short v[28:29], v14, off offset:160
	v_mul_f32_e32 v14, v27, v13
	v_mul_f32_e32 v13, v26, v13
	v_mul_f32_e32 v13, v48, v13
	v_cvt_pk_bf16_f32 v13, v13, s0
	global_store_short v[28:29], v13, off offset:224
	v_mul_f32_e32 v13, 0x4b800000, v12
	v_cndmask_b32_e32 v12, v12, v13, vcc
	v_rsq_f32_e32 v12, v12
	v_mul_f32_e32 v14, v49, v14
	v_cvt_pk_bf16_f32 v14, v14, s0
	global_store_short v[28:29], v14, off offset:192
	v_mul_f32_e32 v13, 0x45800000, v12
	v_cndmask_b32_e32 v14, v12, v13, vcc
	v_lshl_add_u64 v[12:13], s[34:35], 0, v[106:107]
	v_mul_f32_e32 v16, v55, v16
	v_lshlrev_b64 v[12:13], 11, v[12:13]
	v_cvt_pk_bf16_f32 v16, v16, s0
	v_lshl_add_u64 v[12:13], s[36:37], 0, v[12:13]
	global_store_short v[28:29], v16, off
	v_mul_f32_e32 v16, v23, v14
	v_lshl_add_u64 v[4:5], v[12:13], 0, v[4:5]
	v_mul_f32_e32 v12, v15, v14
	v_mul_f32_e32 v11, v11, v14
	v_mul_f32_e32 v10, v10, v14
	v_mul_f32_e32 v9, v9, v14
	v_mul_f32_e32 v8, v8, v14
	v_mul_f32_e32 v7, v7, v14
	v_mul_f32_e32 v6, v6, v14
	v_mul_f32_e32 v16, v55, v16
	v_mul_f32_e32 v12, v54, v12
	v_mul_f32_e32 v11, v53, v11
	v_mul_f32_e32 v10, v52, v10
	v_mul_f32_e32 v9, v51, v9
	v_mul_f32_e32 v8, v50, v8
	v_mul_f32_e32 v7, v49, v7
	v_mul_f32_e32 v6, v48, v6
	v_cvt_pk_bf16_f32 v16, v16, s0
	v_cvt_pk_bf16_f32 v12, v12, s0
	v_cvt_pk_bf16_f32 v11, v11, s0
	v_cvt_pk_bf16_f32 v10, v10, s0
	v_cvt_pk_bf16_f32 v9, v9, s0
	v_cvt_pk_bf16_f32 v8, v8, s0
	v_cvt_pk_bf16_f32 v7, v7, s0
	v_cvt_pk_bf16_f32 v6, v6, s0
	global_store_short v[4:5], v16, off
	global_store_short v[4:5], v12, off offset:32
	global_store_short v[4:5], v11, off offset:64
	global_store_short v[4:5], v10, off offset:96
	global_store_short v[4:5], v9, off offset:128
	global_store_short v[4:5], v8, off offset:160
	global_store_short v[4:5], v7, off offset:192
	global_store_short v[4:5], v6, off offset:224
	s_barrier
	s_cbranch_scc1 .LBB0_632
